# v045 + MLA key loop staggered: waves 4-7 run each trip's row-sum/PV tail after the next barrier, waves 0-3 before it (priority experiment removed)
# speedup vs baseline: 1.0133x; 1.0002x over previous
.LBB0_630:
	s_cmp_ge_u32 s2, 4
	s_cselect_b32 s98, 1, 0
	s_cmpk_lt_i32 s3, 0x200
	s_cselect_b64 s[12:13], -1, 0
	s_cmpk_gt_i32 s3, 0x1ff
	s_cbranch_scc1 .LBB0_674
	s_add_u32 s1, s96, 0x18e00000
	s_addc_u32 s8, s97, 0
	s_add_u32 s4, s96, 0x300000
	s_addc_u32 s5, s97, 0
	s_add_i32 s6, s2, -8
	s_cmp_gt_i32 s2, 20
	s_cselect_b32 s18, s6, s2
	s_cmp_gt_i32 s18, 12
	s_cselect_b64 s[6:7], -1, 0
	s_add_i32 s9, s18, -13
	s_add_i32 s10, s2, 8
	s_cmp_gt_i32 s2, 12
	s_cselect_b32 s20, s2, s10
	s_add_i32 s21, s20, -13
	s_cmp_lt_i32 s20, 13
	s_cselect_b64 s[14:15], -1, 0
	s_and_b64 s[10:11], s[14:15], exec
	s_cselect_b32 s22, s20, s21
	s_cselect_b32 s23, 0, 0x9c00
	s_cselect_b32 s28, s94, 0xbc00
	s_cmp_lt_i32 s18, 13
	s_cselect_b64 s[16:17], -1, 0
	s_and_b64 s[10:11], s[16:17], exec
	s_cselect_b32 s10, s18, s9
	s_cselect_b32 s29, 0, 0x9c00
	s_cselect_b32 s30, s94, 0xbc00
	s_lshl_b32 s31, s10, 10
	s_lshl_b32 s9, s9, 6
	s_lshl_b32 s10, s18, 6
	s_cmp_gt_i32 s20, 12
	s_cselect_b64 s[18:19], -1, 0
	s_lshl_b32 s34, s22, 10
	s_lshl_b32 s11, s21, 6
	s_lshl_b32 s22, s20, 6
	s_cmp_gt_i32 s2, 4
	s_cselect_b32 s20, 8, 16
	s_add_i32 s35, s20, s2
	s_cmp_gt_i32 s35, 12
	s_cselect_b64 s[20:21], -1, 0
	s_add_i32 s33, s35, -13
	s_cmp_lt_i32 s35, 13
	s_cselect_b64 s[24:25], -1, 0
	s_and_b64 s[26:27], s[24:25], exec
	s_cselect_b32 s26, s35, s33
	s_lshl_b32 s26, s26, 10
	s_lshl_b32 s33, s33, 6
	s_lshl_b32 s36, s35, 6
	s_add_u32 s37, s96, 0x15800000
	s_addc_u32 s38, s97, 0
	s_add_u32 s39, s96, 0xb00000
	s_addc_u32 s40, s97, 0
	s_lshl_b32 s27, s2, 12
	s_add_i32 s41, s27, 0
	s_add_i32 s41, s41, 0x11a00
	s_add_i32 s47, s29, 0
	s_add_i32 s48, s23, 0
	s_add_i32 s42, s26, 0
	s_add_i32 s49, s30, 0
	s_add_i32 s50, s28, 0
	s_add_i32 s43, s31, 0
	s_add_i32 s44, s34, 0
	s_add_u32 s45, s96, 0x1fa00000
	s_addc_u32 s46, s97, 0
	s_add_i32 s47, s47, s31
	s_add_i32 s48, s48, s34
	s_add_i32 s49, s49, s31
	s_add_i32 s50, s50, s34
	s_mov_b32 s51, s3
	s_branch .LBB0_633

.Lmla_post2:
	s_add_i32 s60, s60, 1
	s_add_i32 s23, s54, 1
	s_cmp_lg_u32 s54, 2
	s_cselect_b32 s54, s23, 0
	s_add_i32 s23, s55, 1
	s_cmp_lg_u32 s55, 2
	s_cselect_b32 s55, s23, 0
	s_add_i32 s59, s59, 64
	s_cmp_lg_u32 s60, 36
	s_cbranch_scc0 .LBB0_659
	s_cmp_lg_u32 s98, 0
	s_cbranch_scc1 .LBB0_660
.LBB0_659:
	v_add_f32_e32 v100, v177, v178
	v_add_f32_e32 v101, v179, v180
	v_add_f32_e32 v100, v101, v100
	v_add_f32_e32 v101, v181, v182
	v_add_f32_e32 v100, v101, v100
	v_add_f32_e32 v101, v183, v184
	v_add_f32_e32 v100, v101, v100
	v_add_f32_e32 v101, v185, v186
	v_add_f32_e32 v100, v101, v100
	v_add_f32_e32 v101, v187, v188
	v_add_f32_e32 v100, v101, v100
	v_add_f32_e32 v101, v189, v191
	v_add_f32_e32 v100, v101, v100
	v_add_f32_e32 v101, v190, v192
	v_add_f32_e32 v100, v101, v100
	v_fmac_f32_e32 v100, v156, v14
	v_add_f32_e32 v14, v194, v209
	v_add_f32_e32 v101, v195, v104
	v_add_f32_e32 v14, v101, v14
	v_add_f32_e32 v101, v105, v106
	v_add_f32_e32 v14, v101, v14
	v_add_f32_e32 v101, v107, v210
	v_add_f32_e32 v14, v101, v14
	v_add_f32_e32 v88, v88, v89
	v_add_f32_e32 v14, v88, v14
	v_add_f32_e32 v88, v90, v91
	v_add_f32_e32 v14, v88, v14
	v_add_f32_e32 v88, v92, v94
	v_add_f32_e32 v14, v88, v14
	v_add_f32_e32 v88, v93, v95
	v_add_f32_e32 v156, v88, v14
	v_add_f32_e32 v14, v15, v162
	v_add_f32_e32 v15, v160, v163
	v_add_f32_e32 v14, v15, v14
	v_add_f32_e32 v15, v161, v165
	v_add_f32_e32 v14, v15, v14
	v_add_f32_e32 v15, v164, v166
	v_mfma_f32_32x32x16_bf16 v[32:47], v[10:13], v[80:83], v[32:47]
	v_add_f32_e32 v14, v15, v14
	v_add_f32_e32 v15, v167, v171
	v_add_f32_e32 v14, v15, v14
	v_add_f32_e32 v15, v168, v172
	v_add_f32_e32 v14, v15, v14
	v_add_f32_e32 v15, v169, v173
	v_add_f32_e32 v14, v15, v14
	v_mfma_f32_32x32x16_bf16 v[16:31], v[96:99], v[80:83], v[16:31]
	v_add_f32_e32 v15, v170, v174
	v_add_f32_e32 v14, v15, v14
	v_fmac_f32_e32 v14, v159, v0
	v_add_f32_e32 v0, v205, v207
	v_add_f32_e32 v15, v206, v208
	v_add_f32_e32 v0, v15, v0
	v_add_f32_e32 v10, v109, v193
	v_mfma_f32_32x32x16_bf16 v[32:47], v[6:9], v[84:87], v[32:47]
	v_add_f32_e32 v0, v10, v0
	v_add_f32_e32 v10, v111, v196
	v_add_f32_e32 v0, v10, v0
	v_add_f32_e32 v10, v201, v203
	v_add_f32_e32 v0, v10, v0
	v_mfma_f32_32x32x16_bf16 v[16:31], v[2:5], v[84:87], v[16:31]
	v_add_f32_e32 v10, v202, v204
	v_add_f32_e32 v0, v10, v0
	v_add_f32_e32 v10, v197, v199
	v_add_f32_e32 v0, v10, v0
	v_add_f32_e32 v10, v198, v200
	v_add_f32_e32 v159, v10, v0
	v_fmac_f32_e32 v156, v100, v110
	v_fmac_f32_e32 v159, v14, v108
	s_cmp_lg_u32 s60, 36
	s_cbranch_scc0 .LBB0_632
	s_cmp_lg_u32 s98, 0
	s_cbranch_scc1 .LBB0_666

.LBB0_664:
	s_barrier
	s_cmp_gt_u32 s60, 33
	s_cbranch_scc1 .Lmla_hdr_end
	s_cmp_lt_u32 s60, 2
	s_cselect_b32 s23, 8, 11
	s_movk_i32 s34, 0xff00
	s_cselect_b32 s34, 0x8000, s34
	s_lshl_b32 s23, s53, s23
	s_add_i32 s34, s34, s23
	s_add_i32 s34, s59, s34
	s_ashr_i32 s35, s34, 31
	s_lshl_b64 s[68:69], s[34:35], 11
	s_add_u32 s23, s1, s68
	s_addc_u32 s56, s8, s69
	s_lshl_b64 s[34:35], s[34:35], 6
	s_add_u32 s34, s39, s34
	s_addc_u32 s35, s40, s35
	s_lshl_b32 s61, s55, 13
	s_add_i32 s61, s61, 0x9c00
	s_mul_i32 s64, s55, 0x3400
	v_mov_b32_e32 v214, s35
	v_mov_b32_e32 v216, s34
	s_and_b64 s[34:35], s[16:17], exec
	v_mov_b32_e32 v215, s23
	s_cselect_b32 s23, s64, s61
	v_mov_b32_e32 v211, s56
	s_add_i32 m0, s43, s23
	v_cndmask_b32_e64 v213, v211, v214, s[26:27]
	v_cndmask_b32_e64 v212, v215, v216, s[26:27]
	s_and_b64 s[34:35], s[14:15], exec
	v_lshl_add_u64 v[212:213], v[144:145], 1, v[212:213]
	s_cselect_b32 s23, s64, s61
	global_load_lds_dwordx4 v[212:213], off
	v_cndmask_b32_e64 v213, v211, v214, s[28:29]
	v_cndmask_b32_e64 v212, v215, v216, s[28:29]
	s_add_i32 m0, s44, s23
	v_lshl_add_u64 v[212:213], v[146:147], 1, v[212:213]
	s_and_b64 s[34:35], s[24:25], exec
	global_load_lds_dwordx4 v[212:213], off
	v_cndmask_b32_e64 v213, v211, v214, s[30:31]
	v_cndmask_b32_e64 v212, v215, v216, s[30:31]
	s_cselect_b32 s23, s64, s61
	v_lshl_add_u64 v[212:213], v[148:149], 1, v[212:213]
	s_add_i32 m0, s42, s23
	s_nop 0
	global_load_lds_dwordx4 v[212:213], off
.Lmla_hdr_end:
	s_cmp_eq_u32 s98, 0
	s_cbranch_scc1 .LBB0_666
	s_cmp_lg_u32 s60, 0
	s_cbranch_scc1 .LBB0_659

.LBB0_674:
	s_mov_b32 s1, s3
	s_and_b32 s1, s1, 3
	s_cmp_eq_u32 s1, 1
	v_readlane_b32 s6, v255, 58
	s_cselect_b64 s[4:5], -1, 0
	v_readlane_b32 s7, v255, 59
	s_and_b64 s[4:5], s[6:7], s[4:5]
	s_and_b64 vcc, exec, s[4:5]
	s_cbranch_vccz .LBB0_737
	s_cmp_lt_i32 s3, 0
	v_mbcnt_lo_u32_b32 v84, -1, 0
	v_mbcnt_hi_u32_b32 v84, -1, v84
	s_cbranch_scc1 .LBB0_736
	v_readlane_b32 s4, v255, 56
	s_lshl_b32 s1, s3, 3
	s_add_i32 s4, s4, 1
	s_add_i32 s8, s1, s2
	s_bitcmp1_b32 s4, 0
	s_cselect_b32 s1, 0x3e400000, 0
	s_add_u32 s14, s96, s1
	s_addc_u32 s15, s97, 0
	s_cmpk_gt_i32 s8, 0x716f
	v_readlane_b32 s5, v255, 57
	s_cbranch_scc1 .LBB0_729
	s_cmpk_gt_i32 s8, 0xbcf
	s_mov_b64 s[24:25], -1
	s_cbranch_scc0 .LBB0_699
	s_cmpk_gt_u32 s8, 0xc2f
	s_mov_b64 s[20:21], -1
	s_cbranch_scc0 .LBB0_696
	s_cmpk_gt_u32 s8, 0xc6f
	s_cbranch_scc0 .LBB0_693
	s_cmpk_gt_u32 s8, 0xf6f
	s_cbranch_scc0 .LBB0_690
	s_cmpk_gt_u32 s8, 0x116f
	s_cbranch_scc0 .LBB0_687
	s_add_i32 s10, s8, 0xffffee90
	s_lshr_b32 s11, s10, 13
	s_bfe_u32 s9, s10, 0x40009
	s_cmp_eq_u32 s11, 1
	s_movk_i32 s5, 0xc8
	s_cselect_b32 s5, 0xc0, s5
	s_cmpk_gt_u32 s10, 0x1fff
	s_cselect_b32 s5, s5, 0xb8
	v_readlane_b32 s6, v255, 2
	v_readlane_b32 s7, v255, 3
	s_add_u32 s6, s6, s5
	s_addc_u32 s7, s7, 0
	s_load_dwordx2 s[6:7], s[6:7], 0x0
	s_ashr_i32 s5, s4, 31
	s_lshl_b64 s[16:17], s[4:5], 26
	s_waitcnt lgkmcnt(0)
	s_add_u32 s6, s6, s16
	s_addc_u32 s7, s7, s17
	s_lshl_b32 s17, s9, 22
	s_add_u32 s6, s6, s17
	s_addc_u32 s7, s7, 0
	s_lshl_b32 s16, s10, 1
	s_and_b32 s22, s16, 0x3c0
	s_lshl_b32 s16, s22, 12
	s_add_u32 s6, s6, s16
	s_addc_u32 s7, s7, 0
	s_lshl_b32 s16, s10, 5
	s_and_b32 s16, s16, 0x3e0
	s_lshl_b32 s18, s16, 2
	s_add_u32 s6, s6, s18
	s_addc_u32 s7, s7, 0
	s_cmpk_gt_u32 s10, 0x3fff
	s_cbranch_scc0 .LBB0_684
	s_add_u32 s10, s96, s1
	s_addc_u32 s18, s97, 0
	s_lshl_b32 s9, s9, 21
	s_add_u32 s9, s10, s9
	s_addc_u32 s10, s18, 0
	s_lshl_b32 s18, s22, 1
	s_add_u32 s9, s9, s18
	s_addc_u32 s10, s10, 0
	s_add_u32 s18, s9, 0x6000000
	s_addc_u32 s19, s10, 0
	s_mov_b64 s[20:21], 0
